# c7 + dilated-attention item prologue: wait for the Q loads after issuing the first K/V tile loads (counted vmcnt 15..12)
# baseline (speedup 1.0000x reference)
; #define LAS __attribute__((address_space(3)))
;     DI void loadk(int t, bf16x8 (&kn)[4]) const { attn_load_k(P, tokbase, EIN, kcol, 1, 0, SEQ, (rsA + t) * 64 + c0, lane, kn); }
;     DI void loadv(int t, bf16x8 (&vn)[4]) const { attn_load_v(P, tokbase, EIN, vcol, 1, 0, SEQ, (rsA + t) * 64 + c0, lane, vn); }
;     DI void loadk(int T, bf16x8 (&kn)[4]) const { const int sh = sh_of(T); attn_load_k(P, tokbase, EIN, kcol, 1 << sh, r & ((1 << sh) - 1), SEQ >> sh, m0_of(T), lane, kn); }
;     DI void loadv(int T, bf16x8 (&vn)[4]) const { const int sh = sh_of(T); attn_load_v(P, tokbase, EIN, vcol, 1 << sh, r & ((1 << sh) - 1), SEQ >> sh, m0_of(T), lane, vn); }
; template <class Desc>
; DI void attn_loop(const Desc& d, int ntiles, const bf16x8 (&qf)[4], LAS unsigned char* LV, int lane, bf16_t* orow) {
;     ...
;     f32x16 O0, O1;
; #pragma unroll
;     for (int i = 0; i < 16; ++i) { O0[i] = 0.f; O1[i] = 0.f; }
;     float m_run = -1e30f, l_run = 0.f;
;     bf16x8 kA[4], kB[4], vN[4];
;     const int tl = ntiles - 1;
;     d.loadk(0, kA); d.loadv(0, vN); d.loadk(1 < tl ? 1 : tl, kB);
; DI void dil_item(int item, const bf16_t* P, bf16_t* Oo, LAS unsigned char* LV, int lane) {
;     const int mblk = item & 7, r = (item >> 3) & 15, head = (item >> 7) & 7, seq = item >> 10;
;     const size_t tokbase = (size_t)seq * SEQ;
;     const int h = lane >> 5, tq = 16 * (32 * mblk + (lane & 31)) + r;
;     bf16x8 qf[4];
;     { const bf16_t* qp = P + (tokbase + tq) * EIN + 1536 + head * 64 + 8 * h;
; #pragma unroll
;       for (int c = 0; c < 4; ++c) qf[c] = *(const bf16x8*)(qp + 16 * c); }
;     const DilDesc d{P, tokbase, lane, 2048 + head * 64, 2560 + head * 64, mblk, r, tq};
;     attn_loop(d, 33, qf, LV, lane, Oo + (tokbase + tq) * D + 512 + head * 64);
.LBB0_311:
	v_cmp_le_i32_e32 vcc, s84, v113
	v_lshrrev_b32_e32 v5, 1, v113
	v_add_u32_e32 v158, v115, v119
	v_lshlrev_b32_e32 v0, 1, v112
	s_and_saveexec_b64 s[38:39], vcc
	s_xor_b64 s[96:97], exec, s[38:39]
	s_cbranch_execz .LBB0_339
	v_subrev_u32_e32 v2, s84, v113
	v_bfe_u32 v137, v113, 3, 4
	v_lshrrev_b32_e32 v2, 10, v2
	v_mov_b32_e32 v3, v1
	v_lshlrev_b64 v[46:47], 12, v[2:3]
	v_or_b32_e32 v142, v137, v152
	v_or_b32_e32 v134, v46, v142
	v_mov_b64_e32 v[18:19], s[86:87]
	v_mad_u64_u32 v[2:3], s[38:39], v134, s90, v[18:19]
	v_and_b32_e32 v136, 0x1c0, v5
	v_mad_u32_u24 v3, v47, s90, v3
	v_lshlrev_b32_e32 v20, 1, v136
	v_mov_b32_e32 v21, v1
	v_lshl_add_u64 v[2:3], v[2:3], 0, v[20:21]
	v_lshl_add_u64 v[14:15], v[2:3], 0, v[0:1]
	global_load_dwordx4 v[2:5], v[14:15], off offset:3072
	global_load_dwordx4 v[6:9], v[14:15], off offset:3104
	global_load_dwordx4 v[10:13], v[14:15], off offset:3136
	s_nop 0
	global_load_dwordx4 v[14:17], v[14:15], off offset:3168
	v_or_b32_e32 v22, v46, v118
	v_mov_b32_e32 v133, v1
	v_or_b32_e32 v48, 0x1000, v20
	v_lshl_add_u64 v[20:21], s[86:87], 0, v[20:21]
	v_mad_u64_u32 v[22:23], s[38:39], v22, s90, v[18:19]
	v_lshl_add_u64 v[20:21], v[20:21], 0, v[132:133]
	v_or_b32_e32 v28, v46, v128
	s_mov_b64 s[38:39], 0x1400
	v_mov_b32_e32 v49, v1
	v_or_b32_e32 v24, v46, v120
	v_or_b32_e32 v25, v46, v122
	v_or_b32_e32 v26, v46, v124
	v_or_b32_e32 v27, v46, v126
	v_lshl_add_u64 v[138:139], v[20:21], 0, s[38:39]
	v_mad_u64_u32 v[18:19], s[38:39], v28, s90, v[18:19]
	v_mad_u32_u24 v23, v47, s90, v23
	v_mad_u64_u32 v[30:31], s[38:39], v24, s90, v[138:139]
	v_mad_u64_u32 v[32:33], s[38:39], v25, s90, v[138:139]
	v_mad_u64_u32 v[38:39], s[38:39], v26, s90, v[138:139]
	v_mad_u64_u32 v[40:41], s[38:39], v27, s90, v[138:139]
	v_mad_u32_u24 v19, v47, s90, v19
	v_lshl_add_u64 v[20:21], v[22:23], 0, v[48:49]
	v_mad_u32_u24 v31, v47, s90, v31
	v_mad_u32_u24 v33, v47, s90, v33
	v_mad_u32_u24 v39, v47, s90, v39
	v_mad_u32_u24 v41, v47, s90, v41
	v_lshl_add_u64 v[18:19], v[18:19], 0, v[48:49]
	v_lshl_add_u64 v[20:21], v[20:21], 0, v[0:1]
	v_lshl_add_u64 v[50:51], v[18:19], 0, v[0:1]
	v_lshl_add_u64 v[140:141], v[116:117], 0, v[48:49]
	v_mov_b32_e32 v0, v1
	v_mov_b32_e32 v135, v47
	s_mov_b32 s44, 0
	v_mov_b32_e32 v160, 0
	v_mov_b32_e32 v133, 0xf149f2ca
	global_load_dwordx4 v[34:37], v[20:21], off
	global_load_dwordx4 v[26:29], v[20:21], off offset:32
	global_load_dwordx4 v[22:25], v[20:21], off offset:64
	s_nop 0
	global_load_dwordx4 v[18:21], v[20:21], off offset:96
	s_nop 0
	global_load_dwordx4 v[96:99], v[30:31], off
	global_load_dwordx4 v[100:103], v[32:33], off
	global_load_dwordx4 v[104:107], v[38:39], off
	global_load_dwordx4 v[108:111], v[40:41], off
	global_load_dwordx4 v[80:83], v[50:51], off
	global_load_dwordx4 v[42:45], v[50:51], off offset:32
	s_nop 0
	global_load_dwordx4 v[38:41], v[50:51], off offset:64
	global_load_dwordx4 v[30:33], v[50:51], off offset:96
	s_waitcnt vmcnt(15)
	v_mov_b64_e32 v[236:237], v[2:3]
	v_mov_b64_e32 v[238:239], v[4:5]
	s_waitcnt vmcnt(14)
	v_mov_b64_e32 v[240:241], v[6:7]
	v_mov_b64_e32 v[242:243], v[8:9]
	s_waitcnt vmcnt(13)
	v_mov_b64_e32 v[244:245], v[10:11]
	v_mov_b64_e32 v[246:247], v[12:13]
	s_waitcnt vmcnt(12)
	v_mov_b64_e32 v[248:249], v[14:15]
	v_mov_b64_e32 v[250:251], v[16:17]
	v_mov_b32_e32 v14, v1
	v_mov_b32_e32 v15, v1
	v_mov_b32_e32 v2, v1
	v_mov_b32_e32 v3, v1
	v_mov_b32_e32 v4, v1
	v_mov_b32_e32 v5, v1
	v_mov_b32_e32 v6, v1
	v_mov_b32_e32 v7, v1
	v_mov_b32_e32 v8, v1
	v_mov_b32_e32 v9, v1
	v_mov_b32_e32 v10, v1
	v_mov_b32_e32 v11, v1
	v_mov_b32_e32 v12, v1
	v_mov_b32_e32 v13, v1
	v_mov_b64_e32 v[62:63], v[14:15]
	v_mov_b64_e32 v[78:79], v[14:15]
	v_mov_b64_e32 v[60:61], v[12:13]
	v_mov_b64_e32 v[58:59], v[10:11]
	v_mov_b64_e32 v[56:57], v[8:9]
	v_mov_b64_e32 v[54:55], v[6:7]
	v_mov_b64_e32 v[52:53], v[4:5]
	v_mov_b64_e32 v[50:51], v[2:3]
	v_mov_b64_e32 v[48:49], v[0:1]
	v_mov_b64_e32 v[76:77], v[12:13]
	v_mov_b64_e32 v[74:75], v[10:11]
	v_mov_b64_e32 v[72:73], v[8:9]
	v_mov_b64_e32 v[70:71], v[6:7]
	v_mov_b64_e32 v[68:69], v[4:5]
	v_mov_b64_e32 v[66:67], v[2:3]
	v_mov_b64_e32 v[64:65], v[0:1]
	s_branch .LBB0_315
